# v42 plus attention pair loop: QK-start waits no longer wait (vmcnt) on the next pair's LDS-DMA loads; the end-of-pair barrier wait already covers them
# speedup vs baseline: 1.0110x; 1.0110x over previous
; __device__ __forceinline__ void bias_tile_past(f32x16 (&s)[2], float nslope2, float negM0, float dt) {
;     const float slope2 = -nslope2;
; #pragma unroll
;     for (int sub = 0; sub < 2; ++sub) { const float cb = fmaf(nslope2, dt - 32.0f * (float)sub, negM0);
; #pragma unroll
;         for (int i = 0; i < 16; ++i) asm("v_fmamk_f32 %0, %1, %3, %2" : "=v"(s[sub][i]) : "v"(slope2), "v"(cb), "i"(__builtin_bit_cast(int, (float)((i & 3) + 8 * (i >> 2))))); }
; }
; template <bool PAST, bool PAST1 = PAST>
; __device__ __forceinline__ void attn_pair(f32x16 (&o)[4], float& lsum, const bf16x8 (&qf)[4], const LaneAddr& A, unsigned k0, unsigned v0, unsigned k1, unsigned v1, float nslope2, float negM0, float dt0, float dt1) {
;     bf16x8 kf[2][4];
;     f32x16 s0[2], s1[2];
;     bf16x8 pa0[2][2], pa1[2][2];
;     s16x4 vlo[2][4], vhi[2][4];
; #pragma unroll
;     for (int ks = 0; ks < 4; ++ks) { const unsigned ka = A.kb[ks] + k0; kf[0][ks] = *(const ALDS bf16x8*)(size_t)(ka); kf[1][ks] = *(const ALDS bf16x8*)(size_t)(ka + 8192u); }
;     if (PAST) bias_tile_past(s0, nslope2, negM0, dt0); else bias_tile(s0, nslope2, negM0, dt0);
; #pragma unroll
;     for (int ks = 0; ks < 4; ++ks) { MF32(s0[0], kf[0][ks], qf[ks]); MF32(s0[1], kf[1][ks], qf[ks]); }
;     SBAR0();
;     if (PAST1) bias_tile_past(s1, nslope2, negM0, dt1); else bias_tile(s1, nslope2, negM0, dt1);
;     unsigned va0[4][2];
; #pragma unroll
;     for (int et = 0; et < 4; ++et) { va0[et][0] = A.vb[2 * et] + v0; va0[et][1] = A.vb[2 * et + 1] + v0; }
;     bf16x8 k2[2][2];
;     { const unsigned ka = A.kb[0] + k1; k2[0][0] = *(const ALDS bf16x8*)(size_t)(ka); k2[0][1] = *(const ALDS bf16x8*)(size_t)(ka + 8192u); }
;     SBAR0();
; #pragma unroll
;     for (int g = 0; g < 8; ++g) {
;         const int ks = g >> 1, sub = g & 1;
;         if (sub == 0 && ks < 3) { const unsigned ka = A.kb[ks + 1] + k1; k2[(ks + 1) & 1][0] = *(const ALDS bf16x8*)(size_t)(ka); k2[(ks + 1) & 1][1] = *(const ALDS bf16x8*)(size_t)(ka + 8192u); }
;         MF32(s1[sub], k2[ks & 1][sub], qf[ks]);
; #pragma unroll
;         for (int k = 0; k < 4; ++k) { const int idx = 4 * g + k; s0[idx >> 4][idx & 15] = __builtin_amdgcn_exp2f(s0[idx >> 4][idx & 15]); lsum += s0[idx >> 4][idx & 15]; }
;         if (g & 1) pa0[g >> 2][(g >> 1) & 1] = pack8s(s0[g >> 2], 8 * ((g >> 1) & 1));
;         if (g == 6) {
; #pragma unroll
.LBB0_809:
	s_and_b32 s14, s24, 0x10000
	s_add_i32 s73, s14, 0
	v_mad_u64_u32 v[64:65], s[14:15], s70, v211, v[144:145]
	s_add_i32 s14, s73, s84
	v_lshl_add_u64 v[66:67], v[64:65], 0, s[50:51]
	s_mov_b32 s15, m0
	s_mov_b32 m0, s14
	s_nop 0
	global_load_lds_dwordx4 v[66:67], off
	s_mov_b32 m0, s15
	v_lshl_add_u64 v[64:65], v[64:65], 0, s[52:53]
	s_add_i32 s14, s14, 0x8000
	s_mov_b32 s15, m0
	s_mov_b32 m0, s14
	s_nop 0
	global_load_lds_dwordx4 v[64:65], off
	s_mov_b32 m0, s15
	s_add_i32 s72, s24, 0xffff0000
	v_mad_u64_u32 v[64:65], s[14:15], s70, v211, v[146:147]
	s_add_i32 s14, s73, s85
	v_lshl_add_u64 v[66:67], v[64:65], 0, s[50:51]
	s_mov_b32 s15, m0
	s_mov_b32 m0, s14
	s_nop 0
	global_load_lds_dwordx4 v[66:67], off
	s_mov_b32 m0, s15
	v_lshl_add_u64 v[64:65], v[64:65], 0, s[52:53]
	s_add_i32 s14, s14, 0x8000
	s_mov_b32 s15, m0
	s_mov_b32 m0, s14
	s_nop 0
	global_load_lds_dwordx4 v[64:65], off
	s_mov_b32 m0, s15
	v_xor_b32_e32 v197, 0x80000000, v200
	v_mad_u64_u32 v[64:65], s[14:15], s70, v211, v[148:149]
	s_add_i32 s14, s73, s86
	v_lshl_add_u64 v[66:67], v[64:65], 0, s[50:51]
	s_mov_b32 s15, m0
	s_mov_b32 m0, s14
	s_nop 0
	global_load_lds_dwordx4 v[66:67], off
	s_mov_b32 m0, s15
	v_lshl_add_u64 v[64:65], v[64:65], 0, s[52:53]
	s_add_i32 s14, s14, 0x8000
	s_mov_b32 s15, m0
	s_mov_b32 m0, s14
	s_nop 0
	global_load_lds_dwordx4 v[64:65], off
	s_mov_b32 m0, s15
	s_nop 0
	v_mad_u64_u32 v[64:65], s[14:15], s70, v211, v[150:151]
	s_add_i32 s14, s73, s87
	v_lshl_add_u64 v[66:67], v[64:65], 0, s[50:51]
	s_mov_b32 s15, m0
	s_mov_b32 m0, s14
	s_nop 0
	global_load_lds_dwordx4 v[66:67], off
	s_mov_b32 m0, s15
	s_add_i32 s14, s14, 0x8000
	v_lshl_add_u64 v[64:65], v[64:65], 0, s[52:53]
	s_mov_b32 s15, m0
	s_mov_b32 m0, s14
	s_nop 0
	global_load_lds_dwordx4 v[64:65], off
	s_mov_b32 m0, s15
	s_and_b32 s14, s72, 0x10000
	s_add_i32 s72, s14, 0
	v_add_u32_e32 v64, 64, v193
	v_cvt_f32_i32_e32 v68, v64
	v_add_u32_e32 v64, s72, v167
	ds_read_b128 v[70:73], v64
	ds_read_b128 v[64:67], v64 offset:8192
	v_add_u32_e32 v69, s72, v169
	ds_read_b128 v[214:217], v69
	ds_read_b128 v[74:77], v69 offset:8192
	v_add_u32_e32 v69, s72, v171
	ds_read_b128 v[218:221], v69
	ds_read_b128 v[78:81], v69 offset:8192
	v_add_u32_e32 v69, s72, v173
	ds_read_b128 v[222:225], v69
	ds_read_b128 v[82:85], v69 offset:8192
	v_fma_f32 v69, v200, v68, v174
	v_add_f32_e32 v68, 0xc2000000, v68
	v_fmamk_f32 v112, v197, 0, v69
	v_fmamk_f32 v113, v197, 0x3f800000, v69
	v_fmamk_f32 v114, v197, 0x40000000, v69
	v_fmamk_f32 v115, v197, 0x40400000, v69
	v_fmamk_f32 v116, v197, 0x41000000, v69
	v_fmamk_f32 v117, v197, 0x41100000, v69
	v_fmamk_f32 v118, v197, 0x41200000, v69
	v_fmamk_f32 v119, v197, 0x41300000, v69
	v_fmamk_f32 v120, v197, 0x41800000, v69
	v_fmamk_f32 v121, v197, 0x41880000, v69
	v_fmamk_f32 v122, v197, 0x41900000, v69
	v_fmamk_f32 v123, v197, 0x41980000, v69
	v_fmamk_f32 v124, v197, 0x41c00000, v69
	v_fmamk_f32 v125, v197, 0x41c80000, v69
	v_fmamk_f32 v126, v197, 0x41d00000, v69
	v_fmamk_f32 v127, v197, 0x41d80000, v69
	v_fma_f32 v68, v200, v68, v174
	v_fmamk_f32 v96, v197, 0, v68
	v_fmamk_f32 v97, v197, 0x3f800000, v68
	v_fmamk_f32 v98, v197, 0x40000000, v68
	v_fmamk_f32 v99, v197, 0x40400000, v68
	v_fmamk_f32 v100, v197, 0x41000000, v68
	v_fmamk_f32 v101, v197, 0x41100000, v68
	v_fmamk_f32 v102, v197, 0x41200000, v68
	v_fmamk_f32 v103, v197, 0x41300000, v68
	v_fmamk_f32 v104, v197, 0x41800000, v68
	v_fmamk_f32 v105, v197, 0x41880000, v68
	v_fmamk_f32 v106, v197, 0x41900000, v68
	v_fmamk_f32 v107, v197, 0x41980000, v68
	v_fmamk_f32 v108, v197, 0x41c00000, v68
	v_fmamk_f32 v109, v197, 0x41c80000, v68
	v_fmamk_f32 v110, v197, 0x41d00000, v68
	v_fmamk_f32 v111, v197, 0x41d80000, v68
	s_add_i32 s14, s72, 0x8000
	s_waitcnt lgkmcnt(6)
	v_mfma_f32_32x32x16_bf16 v[96:111], v[64:67], v[140:143], v[96:111]
	s_add_i32 s73, s72, 0x4000
	s_add_i32 s72, s72, 0xc000
	v_cvt_f32_i32_e32 v64, v193
	s_waitcnt lgkmcnt(4)
	v_mfma_f32_32x32x16_bf16 v[96:111], v[74:77], v[136:139], v[96:111]
	s_waitcnt lgkmcnt(2)
	v_mfma_f32_32x32x16_bf16 v[96:111], v[78:81], v[132:135], v[96:111]
	s_waitcnt lgkmcnt(0)
	v_mfma_f32_32x32x16_bf16 v[96:111], v[82:85], v[128:131], v[96:111]
	v_mfma_f32_32x32x16_bf16 v[112:127], v[70:73], v[140:143], v[112:127]
	v_fma_f32 v65, v200, v64, v174
	v_add_f32_e32 v64, 0xc2000000, v64
	v_fma_f32 v79, v200, v64, v174
	v_fmamk_f32 v80, v197, 0, v65
	v_fmamk_f32 v81, v197, 0x3f800000, v65
	v_fmamk_f32 v82, v197, 0x40000000, v65
	v_fmamk_f32 v83, v197, 0x40400000, v65
	v_mfma_f32_32x32x16_bf16 v[112:127], v[214:217], v[136:139], v[112:127]
	v_fmamk_f32 v84, v197, 0x41000000, v65
	v_fmamk_f32 v85, v197, 0x41100000, v65
	v_fmamk_f32 v86, v197, 0x41200000, v65
	v_fmamk_f32 v87, v197, 0x41300000, v65
	v_fmamk_f32 v88, v197, 0x41800000, v65
	v_fmamk_f32 v89, v197, 0x41880000, v65
	v_fmamk_f32 v90, v197, 0x41900000, v65
	v_mfma_f32_32x32x16_bf16 v[112:127], v[218:221], v[132:135], v[112:127]
	v_add_u32_e32 v219, s73, v167
	v_fmamk_f32 v91, v197, 0x41980000, v65
	v_fmamk_f32 v92, v197, 0x41c00000, v65
	v_fmamk_f32 v93, v197, 0x41c80000, v65
	v_fmamk_f32 v94, v197, 0x41d00000, v65
	v_fmamk_f32 v95, v197, 0x41d80000, v65
	v_fmamk_f32 v64, v197, 0, v79
	v_fmamk_f32 v65, v197, 0x3f800000, v79
	v_fmamk_f32 v66, v197, 0x40000000, v79
	v_fmamk_f32 v67, v197, 0x40400000, v79
	v_fmamk_f32 v68, v197, 0x41000000, v79
	v_fmamk_f32 v69, v197, 0x41100000, v79
	v_fmamk_f32 v70, v197, 0x41200000, v79
	v_fmamk_f32 v71, v197, 0x41300000, v79
	v_fmamk_f32 v72, v197, 0x41800000, v79
	v_fmamk_f32 v73, v197, 0x41880000, v79
	v_fmamk_f32 v74, v197, 0x41900000, v79
	v_fmamk_f32 v75, v197, 0x41980000, v79
	v_fmamk_f32 v76, v197, 0x41c00000, v79
	v_fmamk_f32 v77, v197, 0x41c80000, v79
	v_fmamk_f32 v78, v197, 0x41d00000, v79
	v_fmamk_f32 v79, v197, 0x41d80000, v79
	ds_read_b128 v[226:229], v219
	ds_read_b128 v[230:233], v219 offset:8192
	v_add_u32_e32 v197, s14, v159
	v_add_u32_e32 v199, s14, v202
	v_add_u32_e32 v213, s14, v161
	v_add_u32_e32 v214, s14, v203
	v_add_u32_e32 v215, s14, v163
	v_add_u32_e32 v216, s14, v204
	v_add_u32_e32 v217, s14, v165
	v_add_u32_e32 v218, s14, v205
	v_mfma_f32_32x32x16_bf16 v[112:127], v[222:225], v[128:131], v[112:127]
	s_nop 11
	v_exp_f32_e32 v112, v112
	v_exp_f32_e32 v113, v113
	v_add_u32_e32 v219, s73, v169
	v_exp_f32_e32 v114, v114
	ds_read_b128 v[220:223], v219
	ds_read_b128 v[234:237], v219 offset:8192
	v_exp_f32_e32 v115, v115
	v_add_f32_e32 v195, v195, v112
	v_add_f32_e32 v195, v113, v195
	v_add_f32_e32 v195, v114, v195
	v_add_f32_e32 v195, v115, v195
	s_waitcnt lgkmcnt(3)
; #define ALDS __attribute__((address_space(3)))
; #define SBAR0() __builtin_amdgcn_sched_barrier(0)
; template <bool PAST, bool PAST1 = PAST>
; __device__ __forceinline__ void attn_pair(f32x16 (&o)[4], float& lsum, const bf16x8 (&qf)[4], const LaneAddr& A, unsigned k0, unsigned v0, unsigned k1, unsigned v1, float nslope2, float negM0, float dt0, float dt1) {
;     ...
; #pragma unroll
;     for (int g = 0; g < 8; ++g) {
;         const int ks = g >> 1, sub = g & 1;
;         if (sub == 0 && ks < 3) { const unsigned ka = A.kb[ks + 1] + k1; k2[(ks + 1) & 1][0] = *(const ALDS bf16x8*)(size_t)(ka); k2[(ks + 1) & 1][1] = *(const ALDS bf16x8*)(size_t)(ka + 8192u); }
;         MF32(s1[sub], k2[ks & 1][sub], qf[ks]);
; #pragma unroll
;         for (int k = 0; k < 4; ++k) { const int idx = 4 * g + k; s0[idx >> 4][idx & 15] = __builtin_amdgcn_exp2f(s0[idx >> 4][idx & 15]); lsum += s0[idx >> 4][idx & 15]; }
;         if (g & 1) pa0[g >> 2][(g >> 1) & 1] = pack8s(s0[g >> 2], 8 * ((g >> 1) & 1));
;         if (g == 6) {
; #pragma unroll
;             for (int et = 0; et < 4; ++et) { TR_ISSUE(vlo[0][et], va0[et][0], 0); TR_ISSUE(vhi[0][et], va0[et][1], 2048); } }
;         SBAR0();
;     }
;     tr_wait<4>(vlo[0], vhi[0]);
;     SBAR0();
;     unsigned va1[4][2];
; #pragma unroll
;     for (int g = 0; g < 16; ++g) {
;         const int step = g >> 2, et = g & 3, cur = step & 1, nxt = cur ^ 1;
;         if (et == 0) {
;             if (step < 3) {
; #pragma unroll
;                 for (int e2 = 0; e2 < 4; ++e2) { TR_ISSUE(vlo[nxt][e2], va0[e2][0], 256 * (32 * ((step + 1) >> 1) + 16 * ((step + 1) & 1))); TR_ISSUE(vhi[nxt][e2], va0[e2][1], 256 * (32 * ((step + 1) >> 1) + 16 * ((step + 1) & 1)) + 2048); }
;             } else {
; #pragma unroll
;                 for (int e2 = 0; e2 < 4; ++e2) { va1[e2][0] = A.vb[2 * e2] + v1; va1[e2][1] = A.vb[2 * e2 + 1] + v1; TR_ISSUE(vlo[nxt][e2], va1[e2][0], 0); TR_ISSUE(vhi[nxt][e2], va1[e2][1], 2048); }
;             }
;         }
;         MF32(o[et], VFRAG(cur, et), pa0[step >> 1][step & 1]);
; #pragma unroll
;         for (int k = 0; k < 2; ++k) { const int idx = 2 * g + k; s1[idx >> 4][idx & 15] = __builtin_amdgcn_exp2f(s1[idx >> 4][idx & 15]); lsum += s1[idx >> 4][idx & 15]; }
;         if (et == 3) { pa1[step >> 1][step & 1] = pack8s(s1[step >> 1], 8 * (step & 1)); tr_wait<4>(vlo[nxt], vhi[nxt]); }
;         SBAR0();
;     }
	v_mfma_f32_32x32x16_bf16 v[80:95], v[226:229], v[140:143], v[80:95]
	v_exp_f32_e32 v219, v116
	v_exp_f32_e32 v224, v118
	v_exp_f32_e32 v119, v119
	s_waitcnt lgkmcnt(2)
	v_mfma_f32_32x32x16_bf16 v[64:79], v[230:233], v[140:143], v[64:79]
	v_add_f32_e32 v116, v219, v195
	v_exp_f32_e32 v195, v117
	v_cvt_pk_bf16_f32 v117, v114, v115
	v_add_f32_e32 v116, v195, v116
	v_add_f32_e32 v116, v224, v116
	v_add_f32_e32 v232, v119, v116
	v_cvt_pk_bf16_f32 v116, v112, v113
	v_cvt_pk_bf16_f32 v118, v219, v195
	v_cvt_pk_bf16_f32 v119, v224, v119
	v_add_u32_e32 v112, s73, v171
	ds_read_b128 v[224:227], v112
	ds_read_b128 v[228:231], v112 offset:8192
	v_exp_f32_e32 v112, v120
	v_exp_f32_e32 v113, v121
	v_exp_f32_e32 v114, v122
	v_exp_f32_e32 v115, v123
	v_add_f32_e32 v120, v112, v232
	v_add_f32_e32 v120, v113, v120
	v_add_f32_e32 v120, v114, v120
	s_waitcnt lgkmcnt(3)
	v_mfma_f32_32x32x16_bf16 v[80:95], v[220:223], v[136:139], v[80:95]
	v_add_f32_e32 v120, v115, v120
	v_exp_f32_e32 v121, v124
	v_exp_f32_e32 v122, v125
	v_exp_f32_e32 v123, v126
	v_exp_f32_e32 v124, v127
	v_add_f32_e32 v120, v121, v120
	v_add_f32_e32 v120, v122, v120
	v_add_f32_e32 v120, v123, v120
	v_add_f32_e32 v195, v124, v120
	s_waitcnt lgkmcnt(2)
	v_mfma_f32_32x32x16_bf16 v[64:79], v[234:237], v[136:139], v[64:79]
	v_cvt_pk_bf16_f32 v112, v112, v113
	v_cvt_pk_bf16_f32 v113, v114, v115
	v_cvt_pk_bf16_f32 v114, v121, v122
	v_cvt_pk_bf16_f32 v115, v123, v124
	v_exp_f32_e32 v96, v96
	v_exp_f32_e32 v97, v97
	v_add_u32_e32 v124, s73, v173
	v_exp_f32_e32 v98, v98
	ds_read_b128 v[120:123], v124
	ds_read_b128 v[124:127], v124 offset:8192
	v_exp_f32_e32 v99, v99
	v_add_f32_e32 v195, v96, v195
	v_add_f32_e32 v195, v97, v195
	v_add_f32_e32 v195, v98, v195
	v_add_f32_e32 v195, v99, v195
	s_waitcnt lgkmcnt(3)
	v_mfma_f32_32x32x16_bf16 v[80:95], v[224:227], v[132:135], v[80:95]
	v_exp_f32_e32 v219, v100
	v_exp_f32_e32 v220, v102
	v_exp_f32_e32 v103, v103
	s_waitcnt lgkmcnt(2)
	v_mfma_f32_32x32x16_bf16 v[64:79], v[228:231], v[132:135], v[64:79]
	v_add_f32_e32 v100, v219, v195
	v_exp_f32_e32 v195, v101
	v_cvt_pk_bf16_f32 v101, v98, v99
	v_add_f32_e32 v100, v195, v100
	v_add_f32_e32 v100, v220, v100
	v_add_f32_e32 v221, v103, v100
	v_cvt_pk_bf16_f32 v100, v96, v97
	v_cvt_pk_bf16_f32 v102, v219, v195
	v_cvt_pk_bf16_f32 v103, v220, v103
	v_exp_f32_e32 v96, v104
	s_waitcnt lgkmcnt(1)
	v_mfma_f32_32x32x16_bf16 v[80:95], v[120:123], v[128:131], v[80:95]
	v_exp_f32_e32 v98, v105
	v_exp_f32_e32 v99, v106
	v_add_f32_e32 v97, v96, v221
	v_exp_f32_e32 v195, v107
	ds_read_b64_tr_b16 v[104:105], v197
	ds_read_b64_tr_b16 v[106:107], v199 offset:2048
	ds_read_b64_tr_b16 v[120:121], v213
	ds_read_b64_tr_b16 v[122:123], v214 offset:2048
	ds_read_b64_tr_b16 v[220:221], v215
	ds_read_b64_tr_b16 v[222:223], v216 offset:2048
	ds_read_b64_tr_b16 v[224:225], v217
	ds_read_b64_tr_b16 v[226:227], v218 offset:2048
	v_add_f32_e32 v97, v98, v97
	v_add_f32_e32 v97, v99, v97
	v_add_f32_e32 v97, v195, v97
	v_exp_f32_e32 v108, v108
	v_exp_f32_e32 v109, v109
	v_exp_f32_e32 v110, v110
	v_exp_f32_e32 v111, v111
	v_add_f32_e32 v97, v108, v97
	v_add_f32_e32 v97, v109, v97
	v_add_f32_e32 v97, v110, v97
	s_waitcnt lgkmcnt(8)
	v_mfma_f32_32x32x16_bf16 v[64:79], v[124:127], v[128:131], v[64:79]
	v_add_f32_e32 v219, v111, v97
	v_cvt_pk_bf16_f32 v96, v96, v98
	v_cvt_pk_bf16_f32 v97, v99, v195
	v_cvt_pk_bf16_f32 v98, v108, v109
	v_cvt_pk_bf16_f32 v99, v110, v111
	ds_read_b64_tr_b16 v[108:109], v197 offset:4096
	ds_read_b64_tr_b16 v[110:111], v199 offset:6144
	ds_read_b64_tr_b16 v[124:125], v213 offset:4096
	ds_read_b64_tr_b16 v[126:127], v214 offset:6144
	ds_read_b64_tr_b16 v[228:229], v215 offset:4096
	ds_read_b64_tr_b16 v[230:231], v216 offset:6144
	ds_read_b64_tr_b16 v[232:233], v217 offset:4096
	ds_read_b64_tr_b16 v[234:235], v218 offset:6144
	s_waitcnt lgkmcnt(14)
	v_mfma_f32_32x32x16_bf16 v[48:63], v[104:107], v[116:119], v[48:63]
	v_exp_f32_e32 v80, v80
	v_exp_f32_e32 v81, v81
	v_add_f32_e32 v104, v80, v219
	v_add_f32_e32 v104, v81, v104
	s_waitcnt lgkmcnt(12)
	v_mfma_f32_32x32x16_bf16 v[32:47], v[120:123], v[116:119], v[32:47]
	v_exp_f32_e32 v82, v82
	v_exp_f32_e32 v83, v83
	v_add_f32_e32 v104, v82, v104
	v_add_f32_e32 v104, v83, v104
	s_waitcnt lgkmcnt(10)
	v_mfma_f32_32x32x16_bf16 v[16:31], v[220:223], v[116:119], v[16:31]
	v_exp_f32_e32 v84, v84
	v_exp_f32_e32 v85, v85
	v_add_f32_e32 v104, v84, v104
	v_add_f32_e32 v104, v85, v104
	s_waitcnt lgkmcnt(8)
	v_mfma_f32_32x32x16_bf16 v[0:15], v[224:227], v[116:119], v[0:15]
	v_exp_f32_e32 v86, v86
	v_exp_f32_e32 v87, v87
	v_cvt_pk_bf16_f32 v80, v80, v81
	v_cvt_pk_bf16_f32 v81, v82, v83
	v_add_f32_e32 v104, v86, v104
	v_add_f32_e32 v195, v87, v104
	v_cvt_pk_bf16_f32 v82, v84, v85
	v_cvt_pk_bf16_f32 v83, v86, v87
	ds_read_b64_tr_b16 v[104:105], v197 offset:8192
	ds_read_b64_tr_b16 v[106:107], v199 offset:10240
	ds_read_b64_tr_b16 v[116:117], v213 offset:8192
	ds_read_b64_tr_b16 v[118:119], v214 offset:10240
	ds_read_b64_tr_b16 v[120:121], v215 offset:8192
	ds_read_b64_tr_b16 v[122:123], v216 offset:10240
	ds_read_b64_tr_b16 v[220:221], v217 offset:8192
	ds_read_b64_tr_b16 v[222:223], v218 offset:10240
	s_waitcnt lgkmcnt(14)
	v_mfma_f32_32x32x16_bf16 v[48:63], v[108:111], v[112:115], v[48:63]
	v_exp_f32_e32 v84, v88
	v_exp_f32_e32 v86, v89
	v_add_f32_e32 v85, v84, v195
	v_add_f32_e32 v85, v86, v85
	s_waitcnt lgkmcnt(12)
	v_mfma_f32_32x32x16_bf16 v[32:47], v[124:127], v[112:115], v[32:47]
	v_exp_f32_e32 v87, v90
	v_exp_f32_e32 v88, v91
	v_add_f32_e32 v85, v87, v85
	v_add_f32_e32 v85, v88, v85
	s_waitcnt lgkmcnt(10)
; template <bool PAST, bool PAST1 = PAST>
; __device__ __forceinline__ void attn_pair(f32x16 (&o)[4], float& lsum, const bf16x8 (&qf)[4], const LaneAddr& A, unsigned k0, unsigned v0, unsigned k1, unsigned v1, float nslope2, float negM0, float dt0, float dt1) {
;     ...
;     unsigned va1[4][2];
; #pragma unroll
;     for (int g = 0; g < 16; ++g) {
;         const int step = g >> 2, et = g & 3, cur = step & 1, nxt = cur ^ 1;
;         if (et == 0) {
;             if (step < 3) {
; #pragma unroll
;                 for (int e2 = 0; e2 < 4; ++e2) { TR_ISSUE(vlo[nxt][e2], va0[e2][0], 256 * (32 * ((step + 1) >> 1) + 16 * ((step + 1) & 1))); TR_ISSUE(vhi[nxt][e2], va0[e2][1], 256 * (32 * ((step + 1) >> 1) + 16 * ((step + 1) & 1)) + 2048); }
;             } else {
; #pragma unroll
;                 for (int e2 = 0; e2 < 4; ++e2) { va1[e2][0] = A.vb[2 * e2] + v1; va1[e2][1] = A.vb[2 * e2 + 1] + v1; TR_ISSUE(vlo[nxt][e2], va1[e2][0], 0); TR_ISSUE(vhi[nxt][e2], va1[e2][1], 2048); }
;             }
;         }
;         MF32(o[et], VFRAG(cur, et), pa0[step >> 1][step & 1]);
; #pragma unroll
;         for (int k = 0; k < 2; ++k) { const int idx = 2 * g + k; s1[idx >> 4][idx & 15] = __builtin_amdgcn_exp2f(s1[idx >> 4][idx & 15]); lsum += s1[idx >> 4][idx & 15]; }
;         if (et == 3) { pa1[step >> 1][step & 1] = pack8s(s1[step >> 1], 8 * (step & 1)); tr_wait<4>(vlo[nxt], vhi[nxt]); }
;         SBAR0();
;     }
;     if (PROBE == 7) { float dmy = negM0;
; #pragma unroll
;         for (int i = 0; i < 64; ++i) asm volatile("v_exp_f32 %0, %0" : "+v"(dmy)); }
;     if (PROBE == 8) { s16x4 dm;
; #pragma unroll
;         for (int i = 0; i < 64; ++i) asm volatile("ds_read_b64_tr_b16 %0, %1 offset:%c2" : "=&v"(dm) : "v"(va1[i & 3][0]), "i"((i >> 2) * 512) : "memory");
;         asm volatile("s_waitcnt lgkmcnt(0)" ::: "memory"); }
; #pragma unroll
;     for (int step = 0; step < 4; ++step) {
;         const int cur = step & 1, nxt = cur ^ 1;
;         if (step < 3) {
; #pragma unroll
;             for (int e2 = 0; e2 < 4; ++e2) { TR_ISSUE(vlo[nxt][e2], va1[e2][0], 256 * (32 * ((step + 1) >> 1) + 16 * ((step + 1) & 1))); TR_ISSUE(vhi[nxt][e2], va1[e2][1], 256 * (32 * ((step + 1) >> 1) + 16 * ((step + 1) & 1)) + 2048); } }
; #pragma unroll
;         for (int et = 0; et < 4; ++et) MF32(o[et], VFRAG(cur, et), pa1[step >> 1][step & 1]);
;         if (step < 3) tr_wait<4>(vlo[nxt], vhi[nxt]);
	v_mfma_f32_32x32x16_bf16 v[16:31], v[228:231], v[112:115], v[16:31]
	v_exp_f32_e32 v89, v92
	v_exp_f32_e32 v90, v93
	v_add_f32_e32 v85, v89, v85
	v_add_f32_e32 v85, v90, v85
	s_waitcnt lgkmcnt(8)
	v_mfma_f32_32x32x16_bf16 v[0:15], v[232:235], v[112:115], v[0:15]
	v_exp_f32_e32 v91, v94
	v_exp_f32_e32 v92, v95
	v_cvt_pk_bf16_f32 v84, v84, v86
	v_cvt_pk_bf16_f32 v86, v89, v90
	v_add_f32_e32 v85, v91, v85
	v_add_f32_e32 v124, v92, v85
	v_cvt_pk_bf16_f32 v85, v87, v88
	v_cvt_pk_bf16_f32 v87, v91, v92
	ds_read_b64_tr_b16 v[88:89], v197 offset:12288
	ds_read_b64_tr_b16 v[90:91], v199 offset:14336
	ds_read_b64_tr_b16 v[92:93], v213 offset:12288
	ds_read_b64_tr_b16 v[94:95], v214 offset:14336
	ds_read_b64_tr_b16 v[108:109], v215 offset:12288
	ds_read_b64_tr_b16 v[110:111], v216 offset:14336
	ds_read_b64_tr_b16 v[112:113], v217 offset:12288
	ds_read_b64_tr_b16 v[114:115], v218 offset:14336
	s_waitcnt lgkmcnt(14)
	v_mfma_f32_32x32x16_bf16 v[48:63], v[104:107], v[100:103], v[48:63]
	v_exp_f32_e32 v64, v64
	v_exp_f32_e32 v65, v65
	v_add_f32_e32 v104, v64, v124
	v_add_f32_e32 v104, v65, v104
	s_waitcnt lgkmcnt(12)
	v_mfma_f32_32x32x16_bf16 v[32:47], v[116:119], v[100:103], v[32:47]
	v_exp_f32_e32 v66, v66
	v_exp_f32_e32 v67, v67
	v_add_f32_e32 v104, v66, v104
	v_add_f32_e32 v104, v67, v104
	s_waitcnt lgkmcnt(10)
	v_mfma_f32_32x32x16_bf16 v[16:31], v[120:123], v[100:103], v[16:31]
	v_exp_f32_e32 v68, v68
	v_exp_f32_e32 v69, v69
	v_add_f32_e32 v104, v68, v104
	v_add_f32_e32 v104, v69, v104
	s_waitcnt lgkmcnt(8)
	v_mfma_f32_32x32x16_bf16 v[0:15], v[220:223], v[100:103], v[0:15]
	v_exp_f32_e32 v70, v70
	v_exp_f32_e32 v71, v71
	v_cvt_pk_bf16_f32 v64, v64, v65
	v_cvt_pk_bf16_f32 v65, v66, v67
	v_add_f32_e32 v100, v70, v104
	v_add_f32_e32 v120, v71, v100
	v_cvt_pk_bf16_f32 v66, v68, v69
	v_cvt_pk_bf16_f32 v67, v70, v71
	s_waitcnt lgkmcnt(6)
	v_mfma_f32_32x32x16_bf16 v[48:63], v[88:91], v[96:99], v[48:63]
	v_exp_f32_e32 v199, v72
	v_add_u32_e32 v121, s72, v159
	v_add_u32_e32 v123, s72, v161
	v_add_u32_e32 v125, s72, v163
	v_add_u32_e32 v127, s72, v165
	v_add_u32_e32 v122, s72, v202
	ds_read_b64_tr_b16 v[68:69], v121
	ds_read_b64_tr_b16 v[70:71], v122 offset:2048
	v_add_u32_e32 v124, s72, v203
	ds_read_b64_tr_b16 v[100:101], v123
	ds_read_b64_tr_b16 v[102:103], v124 offset:2048
	v_add_u32_e32 v126, s72, v204
	ds_read_b64_tr_b16 v[104:105], v125
	ds_read_b64_tr_b16 v[106:107], v126 offset:2048
	v_add_u32_e32 v197, s72, v205
	ds_read_b64_tr_b16 v[116:117], v127
	ds_read_b64_tr_b16 v[118:119], v197 offset:2048
	v_add_f32_e32 v72, v199, v120
	v_exp_f32_e32 v120, v73
	s_nop 0
	v_add_f32_e32 v72, v120, v72
	s_waitcnt lgkmcnt(12)
	v_mfma_f32_32x32x16_bf16 v[32:47], v[92:95], v[96:99], v[32:47]
	v_exp_f32_e32 v92, v74
	v_exp_f32_e32 v93, v75
	v_add_f32_e32 v72, v92, v72
	v_add_f32_e32 v72, v93, v72
	s_waitcnt lgkmcnt(10)
	v_mfma_f32_32x32x16_bf16 v[16:31], v[108:111], v[96:99], v[16:31]
	v_exp_f32_e32 v94, v76
	v_exp_f32_e32 v95, v77
	v_add_f32_e32 v72, v94, v72
	v_add_f32_e32 v72, v95, v72
	s_waitcnt lgkmcnt(8)
	v_mfma_f32_32x32x16_bf16 v[0:15], v[112:115], v[96:99], v[0:15]
	v_exp_f32_e32 v96, v78
	v_exp_f32_e32 v97, v79
	v_add_f32_e32 v72, v96, v72
	v_add_f32_e32 v195, v97, v72
	s_waitcnt lgkmcnt(6)
	v_mfma_f32_32x32x16_bf16 v[48:63], v[68:71], v[80:83], v[48:63]
	ds_read_b64_tr_b16 v[68:69], v121 offset:4096
	ds_read_b64_tr_b16 v[70:71], v122 offset:6144
	ds_read_b64_tr_b16 v[72:73], v123 offset:4096
	ds_read_b64_tr_b16 v[74:75], v124 offset:6144
	ds_read_b64_tr_b16 v[76:77], v125 offset:4096
	ds_read_b64_tr_b16 v[78:79], v126 offset:6144
	ds_read_b64_tr_b16 v[88:89], v127 offset:4096
	ds_read_b64_tr_b16 v[90:91], v197 offset:6144
	s_waitcnt lgkmcnt(12)
	v_mfma_f32_32x32x16_bf16 v[32:47], v[100:103], v[80:83], v[32:47]
	s_waitcnt lgkmcnt(10)
	v_mfma_f32_32x32x16_bf16 v[16:31], v[104:107], v[80:83], v[16:31]
	s_waitcnt lgkmcnt(8)
	v_mfma_f32_32x32x16_bf16 v[0:15], v[116:119], v[80:83], v[0:15]
	s_waitcnt lgkmcnt(6)
	v_mfma_f32_32x32x16_bf16 v[48:63], v[68:71], v[84:87], v[48:63]
	ds_read_b64_tr_b16 v[68:69], v121 offset:8192
	s_waitcnt lgkmcnt(5)
	v_mfma_f32_32x32x16_bf16 v[32:47], v[72:75], v[84:87], v[32:47]
	s_waitcnt lgkmcnt(3)
	v_mfma_f32_32x32x16_bf16 v[16:31], v[76:79], v[84:87], v[16:31]
	ds_read_b64_tr_b16 v[70:71], v122 offset:10240
	ds_read_b64_tr_b16 v[72:73], v123 offset:8192
	ds_read_b64_tr_b16 v[74:75], v124 offset:10240
	ds_read_b64_tr_b16 v[76:77], v125 offset:8192
	ds_read_b64_tr_b16 v[78:79], v126 offset:10240
	ds_read_b64_tr_b16 v[80:81], v127 offset:8192
	ds_read_b64_tr_b16 v[82:83], v197 offset:10240
	s_waitcnt lgkmcnt(8)
	v_mfma_f32_32x32x16_bf16 v[0:15], v[88:91], v[84:87], v[0:15]
	s_waitcnt lgkmcnt(6)
	v_mfma_f32_32x32x16_bf16 v[48:63], v[68:71], v[64:67], v[48:63]
	ds_read_b64_tr_b16 v[68:69], v121 offset:12288
	s_waitcnt lgkmcnt(5)
	v_mfma_f32_32x32x16_bf16 v[32:47], v[72:75], v[64:67], v[32:47]
	s_waitcnt lgkmcnt(3)
	v_mfma_f32_32x32x16_bf16 v[16:31], v[76:79], v[64:67], v[16:31]
	ds_read_b64_tr_b16 v[70:71], v122 offset:14336
	ds_read_b64_tr_b16 v[72:73], v123 offset:12288
	ds_read_b64_tr_b16 v[74:75], v124 offset:14336
	ds_read_b64_tr_b16 v[76:77], v125 offset:12288
	ds_read_b64_tr_b16 v[78:79], v126 offset:14336
	ds_read_b64_tr_b16 v[84:85], v127 offset:12288
	ds_read_b64_tr_b16 v[86:87], v197 offset:14336
	s_waitcnt lgkmcnt(8)
	v_mfma_f32_32x32x16_bf16 v[0:15], v[80:83], v[64:67], v[0:15]
	v_cvt_pk_bf16_f32 v64, v199, v120
	v_cvt_pk_bf16_f32 v65, v92, v93
	v_cvt_pk_bf16_f32 v66, v94, v95
	v_cvt_pk_bf16_f32 v67, v96, v97
	s_waitcnt lgkmcnt(6)
	s_nop 0
	v_mfma_f32_32x32x16_bf16 v[48:63], v[68:71], v[64:67], v[48:63]
	s_waitcnt lgkmcnt(4)
	v_mfma_f32_32x32x16_bf16 v[32:47], v[72:75], v[64:67], v[32:47]
	s_waitcnt lgkmcnt(2)
	v_mfma_f32_32x32x16_bf16 v[16:31], v[76:79], v[64:67], v[16:31]
	s_waitcnt lgkmcnt(0)
	v_mfma_f32_32x32x16_bf16 v[0:15], v[84:87], v[64:67], v[0:15]
	s_waitcnt vmcnt(0) lgkmcnt(0)
	s_barrier
	s_add_i32 s71, s71, -1
	s_add_i32 s24, s24, 0x10000
	s_addk_i32 s70, 0x80
	s_cmp_eq_u32 s71, 0
	v_add_u32_e32 v193, 0xffffff80, v193
	s_cbranch_scc0 .LBB0_809

; __device__ __forceinline__ void bias_tile_past(f32x16 (&s)[2], float nslope2, float negM0, float dt) {
;     const float slope2 = -nslope2;
; #pragma unroll
;     for (int sub = 0; sub < 2; ++sub) { const float cb = fmaf(nslope2, dt - 32.0f * (float)sub, negM0);
; #pragma unroll
;         for (int i = 0; i < 16; ++i) asm("v_fmamk_f32 %0, %1, %3, %2" : "=v"(s[sub][i]) : "v"(slope2), "v"(cb), "i"(__builtin_bit_cast(int, (float)((i & 3) + 8 * (i >> 2))))); }
; }
; template <bool PAST, bool PAST1 = PAST>
; __device__ __forceinline__ void attn_pair(f32x16 (&o)[4], float& lsum, const bf16x8 (&qf)[4], const LaneAddr& A, unsigned k0, unsigned v0, unsigned k1, unsigned v1, float nslope2, float negM0, float dt0, float dt1) {
;     bf16x8 kf[2][4];
;     f32x16 s0[2], s1[2];
;     bf16x8 pa0[2][2], pa1[2][2];
;     s16x4 vlo[2][4], vhi[2][4];
; #pragma unroll
;     for (int ks = 0; ks < 4; ++ks) { const unsigned ka = A.kb[ks] + k0; kf[0][ks] = *(const ALDS bf16x8*)(size_t)(ka); kf[1][ks] = *(const ALDS bf16x8*)(size_t)(ka + 8192u); }
;     if (PAST) bias_tile_past(s0, nslope2, negM0, dt0); else bias_tile(s0, nslope2, negM0, dt0);
; #pragma unroll
;     for (int ks = 0; ks < 4; ++ks) { MF32(s0[0], kf[0][ks], qf[ks]); MF32(s0[1], kf[1][ks], qf[ks]); }
;     SBAR0();
;     if (PAST1) bias_tile_past(s1, nslope2, negM0, dt1); else bias_tile(s1, nslope2, negM0, dt1);
;     unsigned va0[4][2];
; #pragma unroll
;     for (int et = 0; et < 4; ++et) { va0[et][0] = A.vb[2 * et] + v0; va0[et][1] = A.vb[2 * et + 1] + v0; }
;     bf16x8 k2[2][2];
;     { const unsigned ka = A.kb[0] + k1; k2[0][0] = *(const ALDS bf16x8*)(size_t)(ka); k2[0][1] = *(const ALDS bf16x8*)(size_t)(ka + 8192u); }
;     SBAR0();
; #pragma unroll
;     for (int g = 0; g < 8; ++g) {
;         const int ks = g >> 1, sub = g & 1;
;         if (sub == 0 && ks < 3) { const unsigned ka = A.kb[ks + 1] + k1; k2[(ks + 1) & 1][0] = *(const ALDS bf16x8*)(size_t)(ka); k2[(ks + 1) & 1][1] = *(const ALDS bf16x8*)(size_t)(ka + 8192u); }
;         MF32(s1[sub], k2[ks & 1][sub], qf[ks]);
; #pragma unroll
;         for (int k = 0; k < 4; ++k) { const int idx = 4 * g + k; s0[idx >> 4][idx & 15] = __builtin_amdgcn_exp2f(s0[idx >> 4][idx & 15]); lsum += s0[idx >> 4][idx & 15]; }
;         if (g & 1) pa0[g >> 2][(g >> 1) & 1] = pack8s(s0[g >> 2], 8 * ((g >> 1) & 1));
;         if (g == 6) {
; #pragma unroll
.LBB0_1853:
	s_and_b32 s4, s22, 0x10000
	s_add_i32 s67, s4, 0
	v_mad_u64_u32 v[64:65], s[4:5], s64, v211, v[144:145]
	s_add_i32 s4, s67, s84
	v_lshl_add_u64 v[66:67], v[64:65], 0, s[40:41]
	s_mov_b32 s5, m0
	s_mov_b32 m0, s4
	s_nop 0
	global_load_lds_dwordx4 v[66:67], off
	s_mov_b32 m0, s5
	v_lshl_add_u64 v[64:65], v[64:65], 0, s[46:47]
	s_add_i32 s4, s4, 0x8000
	s_mov_b32 s5, m0
	s_mov_b32 m0, s4
	s_nop 0
	global_load_lds_dwordx4 v[64:65], off
	s_mov_b32 m0, s5
	s_add_i32 s66, s22, 0xffff0000
	v_mad_u64_u32 v[64:65], s[4:5], s64, v211, v[146:147]
	s_add_i32 s4, s67, s85
	v_lshl_add_u64 v[66:67], v[64:65], 0, s[40:41]
	s_mov_b32 s5, m0
	s_mov_b32 m0, s4
	s_nop 0
	global_load_lds_dwordx4 v[66:67], off
	s_mov_b32 m0, s5
	v_lshl_add_u64 v[64:65], v[64:65], 0, s[46:47]
	s_add_i32 s4, s4, 0x8000
	s_mov_b32 s5, m0
	s_mov_b32 m0, s4
	s_nop 0
	global_load_lds_dwordx4 v[64:65], off
	s_mov_b32 m0, s5
	v_xor_b32_e32 v197, 0x80000000, v200
	v_mad_u64_u32 v[64:65], s[4:5], s64, v211, v[148:149]
	s_add_i32 s4, s67, s86
	v_lshl_add_u64 v[66:67], v[64:65], 0, s[40:41]
	s_mov_b32 s5, m0
	s_mov_b32 m0, s4
	s_nop 0
	global_load_lds_dwordx4 v[66:67], off
	s_mov_b32 m0, s5
	v_lshl_add_u64 v[64:65], v[64:65], 0, s[46:47]
	s_add_i32 s4, s4, 0x8000
	s_mov_b32 s5, m0
	s_mov_b32 m0, s4
	s_nop 0
	global_load_lds_dwordx4 v[64:65], off
	s_mov_b32 m0, s5
	s_nop 0
	v_mad_u64_u32 v[64:65], s[4:5], s64, v211, v[150:151]
	s_add_i32 s4, s67, s87
	v_lshl_add_u64 v[66:67], v[64:65], 0, s[40:41]
	s_mov_b32 s5, m0
	s_mov_b32 m0, s4
	s_nop 0
	global_load_lds_dwordx4 v[66:67], off
	s_mov_b32 m0, s5
	s_add_i32 s4, s4, 0x8000
	v_lshl_add_u64 v[64:65], v[64:65], 0, s[46:47]
	s_mov_b32 s5, m0
	s_mov_b32 m0, s4
	s_nop 0
	global_load_lds_dwordx4 v[64:65], off
	s_mov_b32 m0, s5
	s_and_b32 s4, s66, 0x10000
	s_add_i32 s66, s4, 0
	v_add_u32_e32 v64, 64, v193
	v_cvt_f32_i32_e32 v68, v64
	v_add_u32_e32 v64, s66, v167
	ds_read_b128 v[70:73], v64
	ds_read_b128 v[64:67], v64 offset:8192
	v_add_u32_e32 v69, s66, v169
	ds_read_b128 v[214:217], v69
	ds_read_b128 v[74:77], v69 offset:8192
	v_add_u32_e32 v69, s66, v171
	ds_read_b128 v[218:221], v69
	ds_read_b128 v[78:81], v69 offset:8192
	v_add_u32_e32 v69, s66, v173
	ds_read_b128 v[222:225], v69
	ds_read_b128 v[82:85], v69 offset:8192
	v_fma_f32 v69, v200, v68, v174
	v_add_f32_e32 v68, 0xc2000000, v68
	v_fmamk_f32 v112, v197, 0, v69
	v_fmamk_f32 v113, v197, 0x3f800000, v69
	v_fmamk_f32 v114, v197, 0x40000000, v69
	v_fmamk_f32 v115, v197, 0x40400000, v69
	v_fmamk_f32 v116, v197, 0x41000000, v69
	v_fmamk_f32 v117, v197, 0x41100000, v69
	v_fmamk_f32 v118, v197, 0x41200000, v69
	v_fmamk_f32 v119, v197, 0x41300000, v69
	v_fmamk_f32 v120, v197, 0x41800000, v69
	v_fmamk_f32 v121, v197, 0x41880000, v69
	v_fmamk_f32 v122, v197, 0x41900000, v69
	v_fmamk_f32 v123, v197, 0x41980000, v69
	v_fmamk_f32 v124, v197, 0x41c00000, v69
	v_fmamk_f32 v125, v197, 0x41c80000, v69
	v_fmamk_f32 v126, v197, 0x41d00000, v69
	v_fmamk_f32 v127, v197, 0x41d80000, v69
	v_fma_f32 v68, v200, v68, v174
	v_fmamk_f32 v96, v197, 0, v68
	v_fmamk_f32 v97, v197, 0x3f800000, v68
	v_fmamk_f32 v98, v197, 0x40000000, v68
	v_fmamk_f32 v99, v197, 0x40400000, v68
	v_fmamk_f32 v100, v197, 0x41000000, v68
	v_fmamk_f32 v101, v197, 0x41100000, v68
	v_fmamk_f32 v102, v197, 0x41200000, v68
	v_fmamk_f32 v103, v197, 0x41300000, v68
	v_fmamk_f32 v104, v197, 0x41800000, v68
	v_fmamk_f32 v105, v197, 0x41880000, v68
	v_fmamk_f32 v106, v197, 0x41900000, v68
	v_fmamk_f32 v107, v197, 0x41980000, v68
	v_fmamk_f32 v108, v197, 0x41c00000, v68
	v_fmamk_f32 v109, v197, 0x41c80000, v68
	v_fmamk_f32 v110, v197, 0x41d00000, v68
	v_fmamk_f32 v111, v197, 0x41d80000, v68
	s_add_i32 s4, s66, 0x8000
	s_waitcnt lgkmcnt(6)
	v_mfma_f32_32x32x16_bf16 v[96:111], v[64:67], v[140:143], v[96:111]
	s_add_i32 s67, s66, 0x4000
	s_add_i32 s66, s66, 0xc000
	v_cvt_f32_i32_e32 v64, v193
	s_waitcnt lgkmcnt(4)
	v_mfma_f32_32x32x16_bf16 v[96:111], v[74:77], v[136:139], v[96:111]
	s_waitcnt lgkmcnt(2)
	v_mfma_f32_32x32x16_bf16 v[96:111], v[78:81], v[132:135], v[96:111]
	s_waitcnt lgkmcnt(0)
	v_mfma_f32_32x32x16_bf16 v[96:111], v[82:85], v[128:131], v[96:111]
	v_mfma_f32_32x32x16_bf16 v[112:127], v[70:73], v[140:143], v[112:127]
	v_fma_f32 v65, v200, v64, v174
	v_add_f32_e32 v64, 0xc2000000, v64
	v_fma_f32 v79, v200, v64, v174
	v_fmamk_f32 v80, v197, 0, v65
	v_fmamk_f32 v81, v197, 0x3f800000, v65
	v_fmamk_f32 v82, v197, 0x40000000, v65
	v_fmamk_f32 v83, v197, 0x40400000, v65
	v_mfma_f32_32x32x16_bf16 v[112:127], v[214:217], v[136:139], v[112:127]
	v_fmamk_f32 v84, v197, 0x41000000, v65
	v_fmamk_f32 v85, v197, 0x41100000, v65
	v_fmamk_f32 v86, v197, 0x41200000, v65
	v_fmamk_f32 v87, v197, 0x41300000, v65
	v_fmamk_f32 v88, v197, 0x41800000, v65
	v_fmamk_f32 v89, v197, 0x41880000, v65
	v_fmamk_f32 v90, v197, 0x41900000, v65
	v_mfma_f32_32x32x16_bf16 v[112:127], v[218:221], v[132:135], v[112:127]
	v_add_u32_e32 v219, s67, v167
	v_fmamk_f32 v91, v197, 0x41980000, v65
	v_fmamk_f32 v92, v197, 0x41c00000, v65
	v_fmamk_f32 v93, v197, 0x41c80000, v65
	v_fmamk_f32 v94, v197, 0x41d00000, v65
	v_fmamk_f32 v95, v197, 0x41d80000, v65
	v_fmamk_f32 v64, v197, 0, v79
	v_fmamk_f32 v65, v197, 0x3f800000, v79
	v_fmamk_f32 v66, v197, 0x40000000, v79
	v_fmamk_f32 v67, v197, 0x40400000, v79
	v_fmamk_f32 v68, v197, 0x41000000, v79
	v_fmamk_f32 v69, v197, 0x41100000, v79
	v_fmamk_f32 v70, v197, 0x41200000, v79
	v_fmamk_f32 v71, v197, 0x41300000, v79
	v_fmamk_f32 v72, v197, 0x41800000, v79
	v_fmamk_f32 v73, v197, 0x41880000, v79
	v_fmamk_f32 v74, v197, 0x41900000, v79
	v_fmamk_f32 v75, v197, 0x41980000, v79
	v_fmamk_f32 v76, v197, 0x41c00000, v79
	v_fmamk_f32 v77, v197, 0x41c80000, v79
	v_fmamk_f32 v78, v197, 0x41d00000, v79
	v_fmamk_f32 v79, v197, 0x41d80000, v79
	ds_read_b128 v[226:229], v219
	ds_read_b128 v[230:233], v219 offset:8192
	v_add_u32_e32 v197, s4, v159
	v_add_u32_e32 v199, s4, v202
	v_add_u32_e32 v213, s4, v161
	v_add_u32_e32 v214, s4, v203
	v_add_u32_e32 v215, s4, v163
	v_add_u32_e32 v216, s4, v204
	v_add_u32_e32 v217, s4, v165
	v_add_u32_e32 v218, s4, v205
	v_mfma_f32_32x32x16_bf16 v[112:127], v[222:225], v[128:131], v[112:127]
	s_nop 11
	v_exp_f32_e32 v112, v112
	v_exp_f32_e32 v113, v113
	v_add_u32_e32 v219, s67, v169
	v_exp_f32_e32 v114, v114
	ds_read_b128 v[220:223], v219
	ds_read_b128 v[234:237], v219 offset:8192
	v_exp_f32_e32 v115, v115
	v_add_f32_e32 v195, v195, v112
	v_add_f32_e32 v195, v113, v195
	v_add_f32_e32 v195, v114, v195
	v_add_f32_e32 v195, v115, v195
	s_waitcnt lgkmcnt(3)
; #define ALDS __attribute__((address_space(3)))
; #define SBAR0() __builtin_amdgcn_sched_barrier(0)
; template <bool PAST, bool PAST1 = PAST>
; __device__ __forceinline__ void attn_pair(f32x16 (&o)[4], float& lsum, const bf16x8 (&qf)[4], const LaneAddr& A, unsigned k0, unsigned v0, unsigned k1, unsigned v1, float nslope2, float negM0, float dt0, float dt1) {
;     ...
; #pragma unroll
;     for (int g = 0; g < 8; ++g) {
;         const int ks = g >> 1, sub = g & 1;
;         if (sub == 0 && ks < 3) { const unsigned ka = A.kb[ks + 1] + k1; k2[(ks + 1) & 1][0] = *(const ALDS bf16x8*)(size_t)(ka); k2[(ks + 1) & 1][1] = *(const ALDS bf16x8*)(size_t)(ka + 8192u); }
;         MF32(s1[sub], k2[ks & 1][sub], qf[ks]);
; #pragma unroll
;         for (int k = 0; k < 4; ++k) { const int idx = 4 * g + k; s0[idx >> 4][idx & 15] = __builtin_amdgcn_exp2f(s0[idx >> 4][idx & 15]); lsum += s0[idx >> 4][idx & 15]; }
;         if (g & 1) pa0[g >> 2][(g >> 1) & 1] = pack8s(s0[g >> 2], 8 * ((g >> 1) & 1));
;         if (g == 6) {
; #pragma unroll
;             for (int et = 0; et < 4; ++et) { TR_ISSUE(vlo[0][et], va0[et][0], 0); TR_ISSUE(vhi[0][et], va0[et][1], 2048); } }
;         SBAR0();
;     }
;     tr_wait<4>(vlo[0], vhi[0]);
;     SBAR0();
;     unsigned va1[4][2];
; #pragma unroll
;     for (int g = 0; g < 16; ++g) {
;         const int step = g >> 2, et = g & 3, cur = step & 1, nxt = cur ^ 1;
;         if (et == 0) {
;             if (step < 3) {
; #pragma unroll
;                 for (int e2 = 0; e2 < 4; ++e2) { TR_ISSUE(vlo[nxt][e2], va0[e2][0], 256 * (32 * ((step + 1) >> 1) + 16 * ((step + 1) & 1))); TR_ISSUE(vhi[nxt][e2], va0[e2][1], 256 * (32 * ((step + 1) >> 1) + 16 * ((step + 1) & 1)) + 2048); }
;             } else {
; #pragma unroll
;                 for (int e2 = 0; e2 < 4; ++e2) { va1[e2][0] = A.vb[2 * e2] + v1; va1[e2][1] = A.vb[2 * e2 + 1] + v1; TR_ISSUE(vlo[nxt][e2], va1[e2][0], 0); TR_ISSUE(vhi[nxt][e2], va1[e2][1], 2048); }
;             }
;         }
;         MF32(o[et], VFRAG(cur, et), pa0[step >> 1][step & 1]);
; #pragma unroll
;         for (int k = 0; k < 2; ++k) { const int idx = 2 * g + k; s1[idx >> 4][idx & 15] = __builtin_amdgcn_exp2f(s1[idx >> 4][idx & 15]); lsum += s1[idx >> 4][idx & 15]; }
;         if (et == 3) { pa1[step >> 1][step & 1] = pack8s(s1[step >> 1], 8 * (step & 1)); tr_wait<4>(vlo[nxt], vhi[nxt]); }
;         SBAR0();
;     }
	v_mfma_f32_32x32x16_bf16 v[80:95], v[226:229], v[140:143], v[80:95]
	v_exp_f32_e32 v219, v116
	v_exp_f32_e32 v224, v118
	v_exp_f32_e32 v119, v119
	s_waitcnt lgkmcnt(2)
	v_mfma_f32_32x32x16_bf16 v[64:79], v[230:233], v[140:143], v[64:79]
	v_add_f32_e32 v116, v219, v195
	v_exp_f32_e32 v195, v117
	v_cvt_pk_bf16_f32 v117, v114, v115
	v_add_f32_e32 v116, v195, v116
	v_add_f32_e32 v116, v224, v116
	v_add_f32_e32 v232, v119, v116
	v_cvt_pk_bf16_f32 v116, v112, v113
	v_cvt_pk_bf16_f32 v118, v219, v195
	v_cvt_pk_bf16_f32 v119, v224, v119
	v_add_u32_e32 v112, s67, v171
	ds_read_b128 v[224:227], v112
	ds_read_b128 v[228:231], v112 offset:8192
	v_exp_f32_e32 v112, v120
	v_exp_f32_e32 v113, v121
	v_exp_f32_e32 v114, v122
	v_exp_f32_e32 v115, v123
	v_add_f32_e32 v120, v112, v232
	v_add_f32_e32 v120, v113, v120
	v_add_f32_e32 v120, v114, v120
	s_waitcnt lgkmcnt(3)
	v_mfma_f32_32x32x16_bf16 v[80:95], v[220:223], v[136:139], v[80:95]
	v_add_f32_e32 v120, v115, v120
	v_exp_f32_e32 v121, v124
	v_exp_f32_e32 v122, v125
	v_exp_f32_e32 v123, v126
	v_exp_f32_e32 v124, v127
	v_add_f32_e32 v120, v121, v120
	v_add_f32_e32 v120, v122, v120
	v_add_f32_e32 v120, v123, v120
	v_add_f32_e32 v195, v124, v120
	s_waitcnt lgkmcnt(2)
	v_mfma_f32_32x32x16_bf16 v[64:79], v[234:237], v[136:139], v[64:79]
	v_cvt_pk_bf16_f32 v112, v112, v113
	v_cvt_pk_bf16_f32 v113, v114, v115
	v_cvt_pk_bf16_f32 v114, v121, v122
	v_cvt_pk_bf16_f32 v115, v123, v124
	v_exp_f32_e32 v96, v96
	v_exp_f32_e32 v97, v97
	v_add_u32_e32 v124, s67, v173
	v_exp_f32_e32 v98, v98
	ds_read_b128 v[120:123], v124
	ds_read_b128 v[124:127], v124 offset:8192
	v_exp_f32_e32 v99, v99
	v_add_f32_e32 v195, v96, v195
	v_add_f32_e32 v195, v97, v195
	v_add_f32_e32 v195, v98, v195
	v_add_f32_e32 v195, v99, v195
	s_waitcnt lgkmcnt(3)
	v_mfma_f32_32x32x16_bf16 v[80:95], v[224:227], v[132:135], v[80:95]
	v_exp_f32_e32 v219, v100
	v_exp_f32_e32 v220, v102
	v_exp_f32_e32 v103, v103
	s_waitcnt lgkmcnt(2)
	v_mfma_f32_32x32x16_bf16 v[64:79], v[228:231], v[132:135], v[64:79]
	v_add_f32_e32 v100, v219, v195
	v_exp_f32_e32 v195, v101
	v_cvt_pk_bf16_f32 v101, v98, v99
	v_add_f32_e32 v100, v195, v100
	v_add_f32_e32 v100, v220, v100
	v_add_f32_e32 v221, v103, v100
	v_cvt_pk_bf16_f32 v100, v96, v97
	v_cvt_pk_bf16_f32 v102, v219, v195
	v_cvt_pk_bf16_f32 v103, v220, v103
	v_exp_f32_e32 v96, v104
	s_waitcnt lgkmcnt(1)
	v_mfma_f32_32x32x16_bf16 v[80:95], v[120:123], v[128:131], v[80:95]
	v_exp_f32_e32 v98, v105
	v_exp_f32_e32 v99, v106
	v_add_f32_e32 v97, v96, v221
	v_exp_f32_e32 v195, v107
	ds_read_b64_tr_b16 v[104:105], v197
	ds_read_b64_tr_b16 v[106:107], v199 offset:2048
	ds_read_b64_tr_b16 v[120:121], v213
	ds_read_b64_tr_b16 v[122:123], v214 offset:2048
	ds_read_b64_tr_b16 v[220:221], v215
	ds_read_b64_tr_b16 v[222:223], v216 offset:2048
	ds_read_b64_tr_b16 v[224:225], v217
	ds_read_b64_tr_b16 v[226:227], v218 offset:2048
	v_add_f32_e32 v97, v98, v97
	v_add_f32_e32 v97, v99, v97
	v_add_f32_e32 v97, v195, v97
	v_exp_f32_e32 v108, v108
	v_exp_f32_e32 v109, v109
	v_exp_f32_e32 v110, v110
	v_exp_f32_e32 v111, v111
	v_add_f32_e32 v97, v108, v97
	v_add_f32_e32 v97, v109, v97
	v_add_f32_e32 v97, v110, v97
	s_waitcnt lgkmcnt(8)
	v_mfma_f32_32x32x16_bf16 v[64:79], v[124:127], v[128:131], v[64:79]
	v_add_f32_e32 v219, v111, v97
	v_cvt_pk_bf16_f32 v96, v96, v98
	v_cvt_pk_bf16_f32 v97, v99, v195
	v_cvt_pk_bf16_f32 v98, v108, v109
	v_cvt_pk_bf16_f32 v99, v110, v111
	ds_read_b64_tr_b16 v[108:109], v197 offset:4096
	ds_read_b64_tr_b16 v[110:111], v199 offset:6144
	ds_read_b64_tr_b16 v[124:125], v213 offset:4096
	ds_read_b64_tr_b16 v[126:127], v214 offset:6144
	ds_read_b64_tr_b16 v[228:229], v215 offset:4096
	ds_read_b64_tr_b16 v[230:231], v216 offset:6144
	ds_read_b64_tr_b16 v[232:233], v217 offset:4096
	ds_read_b64_tr_b16 v[234:235], v218 offset:6144
	s_waitcnt lgkmcnt(14)
	v_mfma_f32_32x32x16_bf16 v[48:63], v[104:107], v[116:119], v[48:63]
	v_exp_f32_e32 v80, v80
	v_exp_f32_e32 v81, v81
	v_add_f32_e32 v104, v80, v219
	v_add_f32_e32 v104, v81, v104
	s_waitcnt lgkmcnt(12)
	v_mfma_f32_32x32x16_bf16 v[32:47], v[120:123], v[116:119], v[32:47]
	v_exp_f32_e32 v82, v82
	v_exp_f32_e32 v83, v83
	v_add_f32_e32 v104, v82, v104
	v_add_f32_e32 v104, v83, v104
	s_waitcnt lgkmcnt(10)
	v_mfma_f32_32x32x16_bf16 v[16:31], v[220:223], v[116:119], v[16:31]
	v_exp_f32_e32 v84, v84
	v_exp_f32_e32 v85, v85
	v_add_f32_e32 v104, v84, v104
	v_add_f32_e32 v104, v85, v104
	s_waitcnt lgkmcnt(8)
	v_mfma_f32_32x32x16_bf16 v[0:15], v[224:227], v[116:119], v[0:15]
	v_exp_f32_e32 v86, v86
	v_exp_f32_e32 v87, v87
	v_cvt_pk_bf16_f32 v80, v80, v81
	v_cvt_pk_bf16_f32 v81, v82, v83
	v_add_f32_e32 v104, v86, v104
	v_add_f32_e32 v195, v87, v104
	v_cvt_pk_bf16_f32 v82, v84, v85
	v_cvt_pk_bf16_f32 v83, v86, v87
	ds_read_b64_tr_b16 v[104:105], v197 offset:8192
	ds_read_b64_tr_b16 v[106:107], v199 offset:10240
	ds_read_b64_tr_b16 v[116:117], v213 offset:8192
	ds_read_b64_tr_b16 v[118:119], v214 offset:10240
	ds_read_b64_tr_b16 v[120:121], v215 offset:8192
	ds_read_b64_tr_b16 v[122:123], v216 offset:10240
	ds_read_b64_tr_b16 v[220:221], v217 offset:8192
	ds_read_b64_tr_b16 v[222:223], v218 offset:10240
	s_waitcnt lgkmcnt(14)
	v_mfma_f32_32x32x16_bf16 v[48:63], v[108:111], v[112:115], v[48:63]
	v_exp_f32_e32 v84, v88
	v_exp_f32_e32 v86, v89
	v_add_f32_e32 v85, v84, v195
	v_add_f32_e32 v85, v86, v85
	s_waitcnt lgkmcnt(12)
	v_mfma_f32_32x32x16_bf16 v[32:47], v[124:127], v[112:115], v[32:47]
	v_exp_f32_e32 v87, v90
	v_exp_f32_e32 v88, v91
	v_add_f32_e32 v85, v87, v85
	v_add_f32_e32 v85, v88, v85
	s_waitcnt lgkmcnt(10)
; template <bool PAST, bool PAST1 = PAST>
; __device__ __forceinline__ void attn_pair(f32x16 (&o)[4], float& lsum, const bf16x8 (&qf)[4], const LaneAddr& A, unsigned k0, unsigned v0, unsigned k1, unsigned v1, float nslope2, float negM0, float dt0, float dt1) {
;     ...
;     unsigned va1[4][2];
; #pragma unroll
;     for (int g = 0; g < 16; ++g) {
;         const int step = g >> 2, et = g & 3, cur = step & 1, nxt = cur ^ 1;
;         if (et == 0) {
;             if (step < 3) {
; #pragma unroll
;                 for (int e2 = 0; e2 < 4; ++e2) { TR_ISSUE(vlo[nxt][e2], va0[e2][0], 256 * (32 * ((step + 1) >> 1) + 16 * ((step + 1) & 1))); TR_ISSUE(vhi[nxt][e2], va0[e2][1], 256 * (32 * ((step + 1) >> 1) + 16 * ((step + 1) & 1)) + 2048); }
;             } else {
; #pragma unroll
;                 for (int e2 = 0; e2 < 4; ++e2) { va1[e2][0] = A.vb[2 * e2] + v1; va1[e2][1] = A.vb[2 * e2 + 1] + v1; TR_ISSUE(vlo[nxt][e2], va1[e2][0], 0); TR_ISSUE(vhi[nxt][e2], va1[e2][1], 2048); }
;             }
;         }
;         MF32(o[et], VFRAG(cur, et), pa0[step >> 1][step & 1]);
; #pragma unroll
;         for (int k = 0; k < 2; ++k) { const int idx = 2 * g + k; s1[idx >> 4][idx & 15] = __builtin_amdgcn_exp2f(s1[idx >> 4][idx & 15]); lsum += s1[idx >> 4][idx & 15]; }
;         if (et == 3) { pa1[step >> 1][step & 1] = pack8s(s1[step >> 1], 8 * (step & 1)); tr_wait<4>(vlo[nxt], vhi[nxt]); }
;         SBAR0();
;     }
;     if (PROBE == 7) { float dmy = negM0;
; #pragma unroll
;         for (int i = 0; i < 64; ++i) asm volatile("v_exp_f32 %0, %0" : "+v"(dmy)); }
;     if (PROBE == 8) { s16x4 dm;
; #pragma unroll
;         for (int i = 0; i < 64; ++i) asm volatile("ds_read_b64_tr_b16 %0, %1 offset:%c2" : "=&v"(dm) : "v"(va1[i & 3][0]), "i"((i >> 2) * 512) : "memory");
;         asm volatile("s_waitcnt lgkmcnt(0)" ::: "memory"); }
; #pragma unroll
;     for (int step = 0; step < 4; ++step) {
;         const int cur = step & 1, nxt = cur ^ 1;
;         if (step < 3) {
; #pragma unroll
;             for (int e2 = 0; e2 < 4; ++e2) { TR_ISSUE(vlo[nxt][e2], va1[e2][0], 256 * (32 * ((step + 1) >> 1) + 16 * ((step + 1) & 1))); TR_ISSUE(vhi[nxt][e2], va1[e2][1], 256 * (32 * ((step + 1) >> 1) + 16 * ((step + 1) & 1)) + 2048); } }
; #pragma unroll
;         for (int et = 0; et < 4; ++et) MF32(o[et], VFRAG(cur, et), pa1[step >> 1][step & 1]);
;         if (step < 3) tr_wait<4>(vlo[nxt], vhi[nxt]);
	v_mfma_f32_32x32x16_bf16 v[16:31], v[228:231], v[112:115], v[16:31]
	v_exp_f32_e32 v89, v92
	v_exp_f32_e32 v90, v93
	v_add_f32_e32 v85, v89, v85
	v_add_f32_e32 v85, v90, v85
	s_waitcnt lgkmcnt(8)
	v_mfma_f32_32x32x16_bf16 v[0:15], v[232:235], v[112:115], v[0:15]
	v_exp_f32_e32 v91, v94
	v_exp_f32_e32 v92, v95
	v_cvt_pk_bf16_f32 v84, v84, v86
	v_cvt_pk_bf16_f32 v86, v89, v90
	v_add_f32_e32 v85, v91, v85
	v_add_f32_e32 v124, v92, v85
	v_cvt_pk_bf16_f32 v85, v87, v88
	v_cvt_pk_bf16_f32 v87, v91, v92
	ds_read_b64_tr_b16 v[88:89], v197 offset:12288
	ds_read_b64_tr_b16 v[90:91], v199 offset:14336
	ds_read_b64_tr_b16 v[92:93], v213 offset:12288
	ds_read_b64_tr_b16 v[94:95], v214 offset:14336
	ds_read_b64_tr_b16 v[108:109], v215 offset:12288
	ds_read_b64_tr_b16 v[110:111], v216 offset:14336
	ds_read_b64_tr_b16 v[112:113], v217 offset:12288
	ds_read_b64_tr_b16 v[114:115], v218 offset:14336
	s_waitcnt lgkmcnt(14)
	v_mfma_f32_32x32x16_bf16 v[48:63], v[104:107], v[100:103], v[48:63]
	v_exp_f32_e32 v64, v64
	v_exp_f32_e32 v65, v65
	v_add_f32_e32 v104, v64, v124
	v_add_f32_e32 v104, v65, v104
	s_waitcnt lgkmcnt(12)
	v_mfma_f32_32x32x16_bf16 v[32:47], v[116:119], v[100:103], v[32:47]
	v_exp_f32_e32 v66, v66
	v_exp_f32_e32 v67, v67
	v_add_f32_e32 v104, v66, v104
	v_add_f32_e32 v104, v67, v104
	s_waitcnt lgkmcnt(10)
	v_mfma_f32_32x32x16_bf16 v[16:31], v[120:123], v[100:103], v[16:31]
	v_exp_f32_e32 v68, v68
	v_exp_f32_e32 v69, v69
	v_add_f32_e32 v104, v68, v104
	v_add_f32_e32 v104, v69, v104
	s_waitcnt lgkmcnt(8)
	v_mfma_f32_32x32x16_bf16 v[0:15], v[220:223], v[100:103], v[0:15]
	v_exp_f32_e32 v70, v70
	v_exp_f32_e32 v71, v71
	v_cvt_pk_bf16_f32 v64, v64, v65
	v_cvt_pk_bf16_f32 v65, v66, v67
	v_add_f32_e32 v100, v70, v104
	v_add_f32_e32 v120, v71, v100
	v_cvt_pk_bf16_f32 v66, v68, v69
	v_cvt_pk_bf16_f32 v67, v70, v71
	s_waitcnt lgkmcnt(6)
	v_mfma_f32_32x32x16_bf16 v[48:63], v[88:91], v[96:99], v[48:63]
	v_exp_f32_e32 v199, v72
	v_add_u32_e32 v121, s66, v159
	v_add_u32_e32 v123, s66, v161
	v_add_u32_e32 v125, s66, v163
	v_add_u32_e32 v127, s66, v165
	v_add_u32_e32 v122, s66, v202
	ds_read_b64_tr_b16 v[68:69], v121
	ds_read_b64_tr_b16 v[70:71], v122 offset:2048
	v_add_u32_e32 v124, s66, v203
	ds_read_b64_tr_b16 v[100:101], v123
	ds_read_b64_tr_b16 v[102:103], v124 offset:2048
	v_add_u32_e32 v126, s66, v204
	ds_read_b64_tr_b16 v[104:105], v125
	ds_read_b64_tr_b16 v[106:107], v126 offset:2048
	v_add_u32_e32 v197, s66, v205
	ds_read_b64_tr_b16 v[116:117], v127
	ds_read_b64_tr_b16 v[118:119], v197 offset:2048
	v_add_f32_e32 v72, v199, v120
	v_exp_f32_e32 v120, v73
	s_nop 0
	v_add_f32_e32 v72, v120, v72
	s_waitcnt lgkmcnt(12)
	v_mfma_f32_32x32x16_bf16 v[32:47], v[92:95], v[96:99], v[32:47]
	v_exp_f32_e32 v92, v74
	v_exp_f32_e32 v93, v75
	v_add_f32_e32 v72, v92, v72
	v_add_f32_e32 v72, v93, v72
	s_waitcnt lgkmcnt(10)
	v_mfma_f32_32x32x16_bf16 v[16:31], v[108:111], v[96:99], v[16:31]
	v_exp_f32_e32 v94, v76
	v_exp_f32_e32 v95, v77
	v_add_f32_e32 v72, v94, v72
	v_add_f32_e32 v72, v95, v72
	s_waitcnt lgkmcnt(8)
	v_mfma_f32_32x32x16_bf16 v[0:15], v[112:115], v[96:99], v[0:15]
	v_exp_f32_e32 v96, v78
	v_exp_f32_e32 v97, v79
	v_add_f32_e32 v72, v96, v72
	v_add_f32_e32 v195, v97, v72
	s_waitcnt lgkmcnt(6)
	v_mfma_f32_32x32x16_bf16 v[48:63], v[68:71], v[80:83], v[48:63]
	ds_read_b64_tr_b16 v[68:69], v121 offset:4096
	ds_read_b64_tr_b16 v[70:71], v122 offset:6144
	ds_read_b64_tr_b16 v[72:73], v123 offset:4096
	ds_read_b64_tr_b16 v[74:75], v124 offset:6144
	ds_read_b64_tr_b16 v[76:77], v125 offset:4096
	ds_read_b64_tr_b16 v[78:79], v126 offset:6144
	ds_read_b64_tr_b16 v[88:89], v127 offset:4096
	ds_read_b64_tr_b16 v[90:91], v197 offset:6144
	s_waitcnt lgkmcnt(12)
	v_mfma_f32_32x32x16_bf16 v[32:47], v[100:103], v[80:83], v[32:47]
	s_waitcnt lgkmcnt(10)
	v_mfma_f32_32x32x16_bf16 v[16:31], v[104:107], v[80:83], v[16:31]
	s_waitcnt lgkmcnt(8)
	v_mfma_f32_32x32x16_bf16 v[0:15], v[116:119], v[80:83], v[0:15]
	s_waitcnt lgkmcnt(6)
	v_mfma_f32_32x32x16_bf16 v[48:63], v[68:71], v[84:87], v[48:63]
	ds_read_b64_tr_b16 v[68:69], v121 offset:8192
	s_waitcnt lgkmcnt(5)
	v_mfma_f32_32x32x16_bf16 v[32:47], v[72:75], v[84:87], v[32:47]
	s_waitcnt lgkmcnt(3)
	v_mfma_f32_32x32x16_bf16 v[16:31], v[76:79], v[84:87], v[16:31]
	ds_read_b64_tr_b16 v[70:71], v122 offset:10240
	ds_read_b64_tr_b16 v[72:73], v123 offset:8192
	ds_read_b64_tr_b16 v[74:75], v124 offset:10240
	ds_read_b64_tr_b16 v[76:77], v125 offset:8192
	ds_read_b64_tr_b16 v[78:79], v126 offset:10240
	ds_read_b64_tr_b16 v[80:81], v127 offset:8192
	ds_read_b64_tr_b16 v[82:83], v197 offset:10240
	s_waitcnt lgkmcnt(8)
	v_mfma_f32_32x32x16_bf16 v[0:15], v[88:91], v[84:87], v[0:15]
	s_waitcnt lgkmcnt(6)
	v_mfma_f32_32x32x16_bf16 v[48:63], v[68:71], v[64:67], v[48:63]
	ds_read_b64_tr_b16 v[68:69], v121 offset:12288
	s_waitcnt lgkmcnt(5)
	v_mfma_f32_32x32x16_bf16 v[32:47], v[72:75], v[64:67], v[32:47]
	s_waitcnt lgkmcnt(3)
	v_mfma_f32_32x32x16_bf16 v[16:31], v[76:79], v[64:67], v[16:31]
	ds_read_b64_tr_b16 v[70:71], v122 offset:14336
	ds_read_b64_tr_b16 v[72:73], v123 offset:12288
	ds_read_b64_tr_b16 v[74:75], v124 offset:14336
	ds_read_b64_tr_b16 v[76:77], v125 offset:12288
	ds_read_b64_tr_b16 v[78:79], v126 offset:14336
	ds_read_b64_tr_b16 v[84:85], v127 offset:12288
	ds_read_b64_tr_b16 v[86:87], v197 offset:14336
	s_waitcnt lgkmcnt(8)
	v_mfma_f32_32x32x16_bf16 v[0:15], v[80:83], v[64:67], v[0:15]
	v_cvt_pk_bf16_f32 v64, v199, v120
	v_cvt_pk_bf16_f32 v65, v92, v93
	v_cvt_pk_bf16_f32 v66, v94, v95
	v_cvt_pk_bf16_f32 v67, v96, v97
	s_waitcnt lgkmcnt(6)
	s_nop 0
	v_mfma_f32_32x32x16_bf16 v[48:63], v[68:71], v[64:67], v[48:63]
	s_waitcnt lgkmcnt(4)
	v_mfma_f32_32x32x16_bf16 v[32:47], v[72:75], v[64:67], v[32:47]
	s_waitcnt lgkmcnt(2)
	v_mfma_f32_32x32x16_bf16 v[16:31], v[76:79], v[64:67], v[16:31]
	s_waitcnt lgkmcnt(0)
	v_mfma_f32_32x32x16_bf16 v[0:15], v[84:87], v[64:67], v[0:15]
	s_waitcnt vmcnt(0) lgkmcnt(0)
	s_barrier
	s_add_i32 s65, s65, -1
	s_add_i32 s22, s22, 0x10000
	s_addk_i32 s64, 0x80
	s_cmp_eq_u32 s65, 0
	v_add_u32_e32 v193, 0xffffff80, v193
	s_cbranch_scc0 .LBB0_1853
